# stack: seam protocol (inv at arrival, poll cross-XCD word), pipelined final RMSNorm, relaxed first-iteration waits in up GEMM
# speedup vs baseline: 1.0078x; 1.0078x over previous
.LBB0_705:
	v_add_u32_e32 v0, 0x10000, v245
	ds_read_b128 v[18:21], v0
	ds_read_b128 v[22:25], v0 offset:1024
	ds_read_b128 v[26:29], v0 offset:2048
	ds_read_b128 v[30:33], v0 offset:3072
	v_add_u32_e32 v0, 0x14000, v245
	ds_read_b128 v[2:5], v0
	ds_read_b128 v[6:9], v0 offset:1024
	ds_read_b128 v[10:13], v0 offset:2048
	ds_read_b128 v[14:17], v0 offset:3072
	ds_read_b128 v[146:149], v249
	ds_read_b128 v[210:213], v249 offset:1024
	ds_read_b128 v[162:165], v249 offset:2048
	ds_read_b128 v[206:209], v249 offset:3072
	ds_read_b128 v[166:169], v249 offset:4096
	ds_read_b128 v[202:205], v249 offset:5120
	ds_read_b128 v[194:197], v249 offset:6144
	ds_read_b128 v[198:201], v249 offset:7168
	s_add_u32 s34, s0, 0x40080
	s_addc_u32 s35, s1, 0
	s_mov_b32 m0, s63
	s_nop 0
	global_load_lds_dwordx4 v252, s[34:35]
	s_and_b64 vcc, exec, s[30:31]
	s_mov_b32 m0, s64
	s_nop 0
	global_load_lds_dwordx4 v254, s[34:35]
	s_mov_b64 s[34:35], -1
	s_cbranch_vccz .LBB0_707
	s_cmp_lg_i32 s75, -2
	s_cbranch_scc1 .Lwup0_n
	s_cmp_lt_u32 s69, 2
	s_cbranch_scc1 .Lwup0_n
	s_waitcnt vmcnt(30)
	s_branch .Lwup0_d

.Lwup0_d:
	s_mov_b64 s[34:35], 0

.LBB0_709:
	s_add_u32 s0, s0, 0x100
	s_addc_u32 s1, s1, 0
	s_waitcnt lgkmcnt(0)
	s_and_b64 s[28:29], s[28:29], exec
	s_cselect_b32 s35, s70, s1
	s_cselect_b32 s34, s71, s0
	s_cselect_b32 s29, s19, s74
	s_cselect_b32 s28, s72, s3
	s_barrier
	s_setprio 1
	s_waitcnt lgkmcnt(0)
	v_mfma_f32_16x16x32_bf16 v[110:113], v[18:21], v[146:149], v[154:157]
	v_mfma_f32_16x16x32_bf16 v[54:57], v[26:29], v[146:149], v[54:57]
	v_mfma_f32_16x16x32_bf16 v[114:117], v[18:21], v[162:165], v[158:161]
	v_mfma_f32_16x16x32_bf16 v[66:69], v[26:29], v[162:165], v[66:69]
	v_mfma_f32_16x16x32_bf16 v[122:125], v[18:21], v[166:169], v[186:189]
	v_mfma_f32_16x16x32_bf16 v[82:85], v[26:29], v[166:169], v[82:85]
	v_mfma_f32_16x16x32_bf16 v[126:129], v[18:21], v[194:197], v[182:185]
	v_mfma_f32_16x16x32_bf16 v[106:109], v[26:29], v[194:197], v[106:109]
	v_mfma_f32_16x16x32_bf16 v[110:113], v[22:25], v[210:213], v[110:113]
	v_mfma_f32_16x16x32_bf16 v[54:57], v[30:33], v[210:213], v[54:57]
	v_mfma_f32_16x16x32_bf16 v[114:117], v[22:25], v[206:209], v[114:117]
	v_mfma_f32_16x16x32_bf16 v[66:69], v[30:33], v[206:209], v[66:69]
	v_mfma_f32_16x16x32_bf16 v[122:125], v[22:25], v[202:205], v[122:125]
	v_mfma_f32_16x16x32_bf16 v[82:85], v[30:33], v[202:205], v[82:85]
	v_mfma_f32_16x16x32_bf16 v[126:129], v[22:25], v[198:201], v[126:129]
	v_mfma_f32_16x16x32_bf16 v[106:109], v[30:33], v[198:201], v[106:109]
	s_setprio 0
	s_setprio 1
	v_mfma_f32_16x16x32_bf16 v[154:157], v[2:5], v[166:169], v[178:181]
	v_mfma_f32_16x16x32_bf16 v[142:145], v[2:5], v[146:149], v[190:193]
	v_mfma_f32_16x16x32_bf16 v[138:141], v[10:13], v[146:149], v[138:141]
	v_mfma_f32_16x16x32_bf16 v[146:149], v[2:5], v[162:165], v[170:173]
	v_mfma_f32_16x16x32_bf16 v[78:81], v[10:13], v[162:165], v[78:81]
	v_mfma_f32_16x16x32_bf16 v[162:165], v[6:9], v[202:205], v[154:157]
	v_mfma_f32_16x16x32_bf16 v[154:157], v[10:13], v[166:169], v[174:177]
	v_mfma_f32_16x16x32_bf16 v[150:153], v[2:5], v[194:197], v[150:153]
	v_mfma_f32_16x16x32_bf16 v[102:105], v[10:13], v[194:197], v[102:105]
	v_mfma_f32_16x16x32_bf16 v[142:145], v[6:9], v[210:213], v[142:145]
	v_mfma_f32_16x16x32_bf16 v[138:141], v[14:17], v[210:213], v[138:141]
	v_mfma_f32_16x16x32_bf16 v[146:149], v[6:9], v[206:209], v[146:149]
	v_mfma_f32_16x16x32_bf16 v[78:81], v[14:17], v[206:209], v[78:81]
	v_mfma_f32_16x16x32_bf16 v[166:169], v[14:17], v[202:205], v[154:157]
	v_mfma_f32_16x16x32_bf16 v[150:153], v[6:9], v[198:201], v[150:153]
	v_mfma_f32_16x16x32_bf16 v[102:105], v[14:17], v[198:201], v[102:105]
	s_setprio 0
	s_barrier
	ds_read_b128 v[186:189], v249 offset:16384
	ds_read_b128 v[190:193], v249 offset:17408
	ds_read_b128 v[178:181], v249 offset:18432
	ds_read_b128 v[182:185], v249 offset:19456
	ds_read_b128 v[170:173], v249 offset:20480
	ds_read_b128 v[174:177], v249 offset:21504
	ds_read_b128 v[154:157], v249 offset:22528
	ds_read_b128 v[158:161], v249 offset:23552
	s_mov_b32 m0, s45
	s_nop 0
	global_load_lds_dwordx4 v253, s[28:29]
	s_add_u32 s36, s28, 0x40000
	s_mov_b32 m0, s46
	s_nop 0
	global_load_lds_dwordx4 v247, s[28:29]
	s_addc_u32 s37, s29, 0
	s_mov_b32 m0, s47
	s_nop 0
	global_load_lds_dwordx4 v253, s[36:37]
	s_and_b64 vcc, exec, s[30:31]
	s_mov_b32 m0, s48
	s_nop 0
	global_load_lds_dwordx4 v247, s[36:37]
	s_mov_b64 s[36:37], -1
	s_mov_b32 m0, s44
	s_nop 0
	global_load_lds_dwordx4 v252, s[34:35]
	s_nop 0
	s_mov_b32 m0, s49
	s_nop 0
	global_load_lds_dwordx4 v254, s[34:35]
	s_cbranch_vccz .LBB0_711
	s_cmp_lg_i32 s75, -2
	s_cbranch_scc1 .Lwup1_n
	s_cmp_lt_u32 s69, 2
	s_cbranch_scc1 .Lwup1_n
	s_waitcnt vmcnt(30)
	s_branch .Lwup1_d

.Lwup1_d:
	s_mov_b64 s[36:37], 0

.LBB0_979:
	s_lshl_b32 s0, s52, 3
	v_readlane_b32 s2, v255, 4
	s_add_i32 s0, s0, s2
	s_cmp_eq_u32 s78, 0x100
	s_cbranch_scc1 .Lfn_fast
	s_movk_i32 s2, 0x98
	s_movk_i32 s3, 0x90
	s_waitcnt lgkmcnt(0)
	s_movk_i32 s4, 0xa0
	s_cmpk_gt_i32 s0, 0x7fff
	s_cbranch_scc1 .LBB0_988
	s_load_dwordx2 s[6:7], s[58:59], s3 offset:0x0
	v_mbcnt_lo_u32_b32 v0, -1, s1
	s_waitcnt vmcnt(0)
	v_mbcnt_hi_u32_b32 v16, -1, v0
	v_ashrrev_i32_e32 v17, 31, v16
	v_lshlrev_b64 v[18:19], 4, v[16:17]
	s_load_dwordx2 s[4:5], s[58:59], s4 offset:0x0
	s_waitcnt lgkmcnt(0)
	v_lshl_add_u64 v[20:21], s[6:7], 0, v[18:19]
	global_load_dwordx4 v[0:3], v[20:21], off
	global_load_dwordx4 v[4:7], v[20:21], off offset:1024
	global_load_dwordx4 v[8:11], v[20:21], off offset:2048
	global_load_dwordx4 v[12:15], v[20:21], off offset:3072
	s_load_dwordx2 s[2:3], s[58:59], s2 offset:0x0
	s_lshl_b32 s14, s78, 3
	s_add_u32 s15, s4, 0x3300000
	s_addc_u32 s16, s5, 0
	v_lshl_add_u64 v[16:17], v[16:17], 3, s[4:5]
	s_mov_b64 s[4:5], 0x6100000
	v_lshl_add_u64 v[28:29], v[16:17], 0, s[4:5]
	s_waitcnt lgkmcnt(0)
	v_lshl_add_u64 v[30:31], s[2:3], 0, v[18:19]
	s_lshl_b32 s17, s78, 5
	s_lshl_b32 s18, s78, 4
	s_mul_i32 s19, s78, 24
	v_mov_b32_e32 v56, 0
	v_mov_b32_e32 v57, 0x358637bd
	s_branch .LBB0_982

.Lfn_fast:
	s_load_dwordx2 s[6:7], s[58:59], 0x90
	s_load_dwordx2 s[4:5], s[58:59], 0xa0
	s_load_dwordx2 s[2:3], s[58:59], 0x98
	v_mbcnt_lo_u32_b32 v16, -1, 0
	v_mbcnt_hi_u32_b32 v16, -1, v16
	v_lshlrev_b32_e32 v17, 3, v16
	v_lshlrev_b32_e32 v18, 4, v16
	v_mov_b32_e32 v19, 0
	v_mov_b32_e32 v20, 0x358637bd
	s_waitcnt lgkmcnt(0)
	global_load_dwordx4 v[0:3], v18, s[6:7] offset:0
	global_load_dwordx4 v[4:7], v18, s[6:7] offset:1024
	global_load_dwordx4 v[8:11], v18, s[6:7] offset:2048
	global_load_dwordx4 v[12:15], v18, s[6:7] offset:3072
	s_lshl_b32 s8, s0, 11
	s_add_u32 s10, s4, s8
	s_addc_u32 s11, s5, 0
	s_add_u32 s10, s10, 0x6100000
	s_addc_u32 s11, s11, 0
	s_lshl_b32 s8, s0, 4
	s_add_u32 s12, s4, s8
	s_addc_u32 s13, s5, 0
	s_add_u32 s12, s12, 0x3300000
	s_addc_u32 s13, s13, 0
	s_lshl_b32 s8, s0, 12
	s_add_u32 s14, s2, s8
	s_addc_u32 s15, s3, 0
	s_waitcnt vmcnt(0)
	global_load_dwordx2 v[32:33], v17, s[10:11] offset:0
	global_load_dwordx2 v[34:35], v17, s[10:11] offset:512
	global_load_dwordx2 v[36:37], v17, s[10:11] offset:1024
	global_load_dwordx2 v[38:39], v17, s[10:11] offset:1536
	global_load_dwordx4 v[40:43], v19, s[12:13]
	s_add_u32 s10, s10, 0x400000
	s_addc_u32 s11, s11, 0
	s_add_u32 s12, s12, 0x8000
	s_addc_u32 s13, s13, 0
	global_load_dwordx2 v[44:45], v17, s[10:11] offset:0
	global_load_dwordx2 v[46:47], v17, s[10:11] offset:512
	global_load_dwordx2 v[48:49], v17, s[10:11] offset:1024
	global_load_dwordx2 v[50:51], v17, s[10:11] offset:1536
	global_load_dwordx4 v[52:55], v19, s[12:13]
	s_add_u32 s10, s10, 0x400000
	s_addc_u32 s11, s11, 0
	s_add_u32 s12, s12, 0x8000
	s_addc_u32 s13, s13, 0
	global_load_dwordx2 v[56:57], v17, s[10:11] offset:0
	global_load_dwordx2 v[58:59], v17, s[10:11] offset:512
	global_load_dwordx2 v[60:61], v17, s[10:11] offset:1024
	global_load_dwordx2 v[62:63], v17, s[10:11] offset:1536
	global_load_dwordx4 v[64:67], v19, s[12:13]
	s_add_u32 s10, s10, 0x400000
	s_addc_u32 s11, s11, 0
	s_add_u32 s12, s12, 0x8000
	s_addc_u32 s13, s13, 0
	global_load_dwordx2 v[68:69], v17, s[10:11] offset:0
	global_load_dwordx2 v[70:71], v17, s[10:11] offset:512
	global_load_dwordx2 v[72:73], v17, s[10:11] offset:1024
	global_load_dwordx2 v[74:75], v17, s[10:11] offset:1536
	global_load_dwordx4 v[76:79], v19, s[12:13]
	s_add_u32 s10, s10, 0x400000
	s_addc_u32 s11, s11, 0
	s_add_u32 s12, s12, 0x8000
	s_addc_u32 s13, s13, 0
	global_load_dwordx2 v[80:81], v17, s[10:11] offset:0
	global_load_dwordx2 v[82:83], v17, s[10:11] offset:512
	global_load_dwordx2 v[84:85], v17, s[10:11] offset:1024
	global_load_dwordx2 v[86:87], v17, s[10:11] offset:1536
	global_load_dwordx4 v[88:91], v19, s[12:13]
	s_add_u32 s10, s10, 0x400000
	s_addc_u32 s11, s11, 0
	s_add_u32 s12, s12, 0x8000
	s_addc_u32 s13, s13, 0
	global_load_dwordx2 v[92:93], v17, s[10:11] offset:0
	global_load_dwordx2 v[94:95], v17, s[10:11] offset:512
	global_load_dwordx2 v[96:97], v17, s[10:11] offset:1024
	global_load_dwordx2 v[98:99], v17, s[10:11] offset:1536
	global_load_dwordx4 v[100:103], v19, s[12:13]
	s_add_u32 s10, s10, 0x400000
	s_addc_u32 s11, s11, 0
	s_add_u32 s12, s12, 0x8000
	s_addc_u32 s13, s13, 0
	s_waitcnt vmcnt(20)
	global_load_dwordx2 v[104:105], v17, s[10:11] offset:0
	global_load_dwordx2 v[106:107], v17, s[10:11] offset:512
	global_load_dwordx2 v[108:109], v17, s[10:11] offset:1024
	global_load_dwordx2 v[110:111], v17, s[10:11] offset:1536
	global_load_dwordx4 v[112:115], v19, s[12:13]
	s_add_u32 s10, s10, 0x400000
	s_addc_u32 s11, s11, 0
	s_add_u32 s12, s12, 0x8000
	s_addc_u32 s13, s13, 0
	global_load_dwordx2 v[116:117], v17, s[10:11] offset:0
	global_load_dwordx2 v[118:119], v17, s[10:11] offset:512
	global_load_dwordx2 v[120:121], v17, s[10:11] offset:1024
	global_load_dwordx2 v[122:123], v17, s[10:11] offset:1536
	global_load_dwordx4 v[124:127], v19, s[12:13]
	s_add_u32 s10, s10, 0x400000
	s_addc_u32 s11, s11, 0
	s_add_u32 s12, s12, 0x8000
	s_addc_u32 s13, s13, 0
	v_add_f32_e32 v128, v40, v41
	v_add_f32_e32 v129, v42, v43
	v_add_f32_e32 v128, v128, v129
	v_fmamk_f32 v128, v128, 0x3a800000, v20
	v_rsq_f32_e32 v130, v128
	v_lshlrev_b32_e32 v132, 16, v32
	v_and_b32_e32 v133, 0xffff0000, v32
	v_lshlrev_b32_e32 v134, 16, v33
	v_and_b32_e32 v135, 0xffff0000, v33
	v_pk_mul_f32 v[132:133], v[130:131], v[132:133] op_sel_hi:[0,1]
	v_pk_mul_f32 v[134:135], v[130:131], v[134:135] op_sel_hi:[0,1]
	v_pk_mul_f32 v[136:137], v[132:133], v[0:1]
	v_pk_mul_f32 v[138:139], v[134:135], v[2:3]
	v_lshlrev_b32_e32 v132, 16, v34
	v_and_b32_e32 v133, 0xffff0000, v34
	v_lshlrev_b32_e32 v134, 16, v35
	v_and_b32_e32 v135, 0xffff0000, v35
	v_pk_mul_f32 v[132:133], v[130:131], v[132:133] op_sel_hi:[0,1]
	v_pk_mul_f32 v[134:135], v[130:131], v[134:135] op_sel_hi:[0,1]
	v_pk_mul_f32 v[140:141], v[132:133], v[4:5]
	v_pk_mul_f32 v[142:143], v[134:135], v[6:7]
	v_lshlrev_b32_e32 v132, 16, v36
	v_and_b32_e32 v133, 0xffff0000, v36
	v_lshlrev_b32_e32 v134, 16, v37
	v_and_b32_e32 v135, 0xffff0000, v37
	v_pk_mul_f32 v[132:133], v[130:131], v[132:133] op_sel_hi:[0,1]
	v_pk_mul_f32 v[134:135], v[130:131], v[134:135] op_sel_hi:[0,1]
	v_pk_mul_f32 v[144:145], v[132:133], v[8:9]
	v_pk_mul_f32 v[146:147], v[134:135], v[10:11]
	v_lshlrev_b32_e32 v132, 16, v38
	v_and_b32_e32 v133, 0xffff0000, v38
	v_lshlrev_b32_e32 v134, 16, v39
	v_and_b32_e32 v135, 0xffff0000, v39
	v_pk_mul_f32 v[132:133], v[130:131], v[132:133] op_sel_hi:[0,1]
	v_pk_mul_f32 v[134:135], v[130:131], v[134:135] op_sel_hi:[0,1]
	v_pk_mul_f32 v[148:149], v[132:133], v[12:13]
	v_pk_mul_f32 v[150:151], v[134:135], v[14:15]
	global_store_dwordx4 v18, v[136:139], s[14:15] offset:0
	global_store_dwordx4 v18, v[140:143], s[14:15] offset:1024
	global_store_dwordx4 v18, v[144:147], s[14:15] offset:2048
	global_store_dwordx4 v18, v[148:151], s[14:15] offset:3072
	s_add_u32 s14, s14, 0x800000
	s_addc_u32 s15, s15, 0
	s_nop 1
	v_add_f32_e32 v128, v52, v53
	v_add_f32_e32 v129, v54, v55
	v_add_f32_e32 v128, v128, v129
	v_fmamk_f32 v128, v128, 0x3a800000, v20
	v_rsq_f32_e32 v130, v128
	v_lshlrev_b32_e32 v132, 16, v44
	v_and_b32_e32 v133, 0xffff0000, v44
	v_lshlrev_b32_e32 v134, 16, v45
	v_and_b32_e32 v135, 0xffff0000, v45
	v_pk_mul_f32 v[132:133], v[130:131], v[132:133] op_sel_hi:[0,1]
	v_pk_mul_f32 v[134:135], v[130:131], v[134:135] op_sel_hi:[0,1]
	v_pk_mul_f32 v[136:137], v[132:133], v[0:1]
	v_pk_mul_f32 v[138:139], v[134:135], v[2:3]
	v_lshlrev_b32_e32 v132, 16, v46
	v_and_b32_e32 v133, 0xffff0000, v46
	v_lshlrev_b32_e32 v134, 16, v47
	v_and_b32_e32 v135, 0xffff0000, v47
	v_pk_mul_f32 v[132:133], v[130:131], v[132:133] op_sel_hi:[0,1]
	v_pk_mul_f32 v[134:135], v[130:131], v[134:135] op_sel_hi:[0,1]
	v_pk_mul_f32 v[140:141], v[132:133], v[4:5]
	v_pk_mul_f32 v[142:143], v[134:135], v[6:7]
	v_lshlrev_b32_e32 v132, 16, v48
	v_and_b32_e32 v133, 0xffff0000, v48
	v_lshlrev_b32_e32 v134, 16, v49
	v_and_b32_e32 v135, 0xffff0000, v49
	v_pk_mul_f32 v[132:133], v[130:131], v[132:133] op_sel_hi:[0,1]
	v_pk_mul_f32 v[134:135], v[130:131], v[134:135] op_sel_hi:[0,1]
	v_pk_mul_f32 v[144:145], v[132:133], v[8:9]
	v_pk_mul_f32 v[146:147], v[134:135], v[10:11]
	v_lshlrev_b32_e32 v132, 16, v50
	v_and_b32_e32 v133, 0xffff0000, v50
	v_lshlrev_b32_e32 v134, 16, v51
	v_and_b32_e32 v135, 0xffff0000, v51
	v_pk_mul_f32 v[132:133], v[130:131], v[132:133] op_sel_hi:[0,1]
	v_pk_mul_f32 v[134:135], v[130:131], v[134:135] op_sel_hi:[0,1]
	v_pk_mul_f32 v[148:149], v[132:133], v[12:13]
	v_pk_mul_f32 v[150:151], v[134:135], v[14:15]
	global_store_dwordx4 v18, v[136:139], s[14:15] offset:0
	global_store_dwordx4 v18, v[140:143], s[14:15] offset:1024
	global_store_dwordx4 v18, v[144:147], s[14:15] offset:2048
	global_store_dwordx4 v18, v[148:151], s[14:15] offset:3072
	s_add_u32 s14, s14, 0x800000
	s_addc_u32 s15, s15, 0
	s_nop 1
	s_waitcnt vmcnt(28)
	global_load_dwordx2 v[32:33], v17, s[10:11] offset:0
	global_load_dwordx2 v[34:35], v17, s[10:11] offset:512
	global_load_dwordx2 v[36:37], v17, s[10:11] offset:1024
	global_load_dwordx2 v[38:39], v17, s[10:11] offset:1536
	global_load_dwordx4 v[40:43], v19, s[12:13]
	s_add_u32 s10, s10, 0x400000
	s_addc_u32 s11, s11, 0
	s_add_u32 s12, s12, 0x8000
	s_addc_u32 s13, s13, 0
	global_load_dwordx2 v[44:45], v17, s[10:11] offset:0
	global_load_dwordx2 v[46:47], v17, s[10:11] offset:512
	global_load_dwordx2 v[48:49], v17, s[10:11] offset:1024
	global_load_dwordx2 v[50:51], v17, s[10:11] offset:1536
	global_load_dwordx4 v[52:55], v19, s[12:13]
	s_add_u32 s10, s10, 0x400000
	s_addc_u32 s11, s11, 0
	s_add_u32 s12, s12, 0x8000
	s_addc_u32 s13, s13, 0
	v_add_f32_e32 v128, v64, v65
	v_add_f32_e32 v129, v66, v67
	v_add_f32_e32 v128, v128, v129
	v_fmamk_f32 v128, v128, 0x3a800000, v20
	v_rsq_f32_e32 v130, v128
	v_lshlrev_b32_e32 v132, 16, v56
	v_and_b32_e32 v133, 0xffff0000, v56
	v_lshlrev_b32_e32 v134, 16, v57
	v_and_b32_e32 v135, 0xffff0000, v57
	v_pk_mul_f32 v[132:133], v[130:131], v[132:133] op_sel_hi:[0,1]
	v_pk_mul_f32 v[134:135], v[130:131], v[134:135] op_sel_hi:[0,1]
	v_pk_mul_f32 v[136:137], v[132:133], v[0:1]
	v_pk_mul_f32 v[138:139], v[134:135], v[2:3]
	v_lshlrev_b32_e32 v132, 16, v58
	v_and_b32_e32 v133, 0xffff0000, v58
	v_lshlrev_b32_e32 v134, 16, v59
	v_and_b32_e32 v135, 0xffff0000, v59
	v_pk_mul_f32 v[132:133], v[130:131], v[132:133] op_sel_hi:[0,1]
	v_pk_mul_f32 v[134:135], v[130:131], v[134:135] op_sel_hi:[0,1]
	v_pk_mul_f32 v[140:141], v[132:133], v[4:5]
	v_pk_mul_f32 v[142:143], v[134:135], v[6:7]
	v_lshlrev_b32_e32 v132, 16, v60
	v_and_b32_e32 v133, 0xffff0000, v60
	v_lshlrev_b32_e32 v134, 16, v61
	v_and_b32_e32 v135, 0xffff0000, v61
	v_pk_mul_f32 v[132:133], v[130:131], v[132:133] op_sel_hi:[0,1]
	v_pk_mul_f32 v[134:135], v[130:131], v[134:135] op_sel_hi:[0,1]
	v_pk_mul_f32 v[144:145], v[132:133], v[8:9]
	v_pk_mul_f32 v[146:147], v[134:135], v[10:11]
	v_lshlrev_b32_e32 v132, 16, v62
	v_and_b32_e32 v133, 0xffff0000, v62
	v_lshlrev_b32_e32 v134, 16, v63
	v_and_b32_e32 v135, 0xffff0000, v63
	v_pk_mul_f32 v[132:133], v[130:131], v[132:133] op_sel_hi:[0,1]
	v_pk_mul_f32 v[134:135], v[130:131], v[134:135] op_sel_hi:[0,1]
	v_pk_mul_f32 v[148:149], v[132:133], v[12:13]
	v_pk_mul_f32 v[150:151], v[134:135], v[14:15]
	global_store_dwordx4 v18, v[136:139], s[14:15] offset:0
	global_store_dwordx4 v18, v[140:143], s[14:15] offset:1024
	global_store_dwordx4 v18, v[144:147], s[14:15] offset:2048
	global_store_dwordx4 v18, v[148:151], s[14:15] offset:3072
	s_add_u32 s14, s14, 0x800000
	s_addc_u32 s15, s15, 0
	s_nop 1
	v_add_f32_e32 v128, v76, v77
	v_add_f32_e32 v129, v78, v79
	v_add_f32_e32 v128, v128, v129
	v_fmamk_f32 v128, v128, 0x3a800000, v20
	v_rsq_f32_e32 v130, v128
	v_lshlrev_b32_e32 v132, 16, v68
	v_and_b32_e32 v133, 0xffff0000, v68
	v_lshlrev_b32_e32 v134, 16, v69
	v_and_b32_e32 v135, 0xffff0000, v69
	v_pk_mul_f32 v[132:133], v[130:131], v[132:133] op_sel_hi:[0,1]
	v_pk_mul_f32 v[134:135], v[130:131], v[134:135] op_sel_hi:[0,1]
	v_pk_mul_f32 v[136:137], v[132:133], v[0:1]
	v_pk_mul_f32 v[138:139], v[134:135], v[2:3]
	v_lshlrev_b32_e32 v132, 16, v70
	v_and_b32_e32 v133, 0xffff0000, v70
	v_lshlrev_b32_e32 v134, 16, v71
	v_and_b32_e32 v135, 0xffff0000, v71
	v_pk_mul_f32 v[132:133], v[130:131], v[132:133] op_sel_hi:[0,1]
	v_pk_mul_f32 v[134:135], v[130:131], v[134:135] op_sel_hi:[0,1]
	v_pk_mul_f32 v[140:141], v[132:133], v[4:5]
	v_pk_mul_f32 v[142:143], v[134:135], v[6:7]
	v_lshlrev_b32_e32 v132, 16, v72
	v_and_b32_e32 v133, 0xffff0000, v72
	v_lshlrev_b32_e32 v134, 16, v73
	v_and_b32_e32 v135, 0xffff0000, v73
	v_pk_mul_f32 v[132:133], v[130:131], v[132:133] op_sel_hi:[0,1]
	v_pk_mul_f32 v[134:135], v[130:131], v[134:135] op_sel_hi:[0,1]
	v_pk_mul_f32 v[144:145], v[132:133], v[8:9]
	v_pk_mul_f32 v[146:147], v[134:135], v[10:11]
	v_lshlrev_b32_e32 v132, 16, v74
	v_and_b32_e32 v133, 0xffff0000, v74
	v_lshlrev_b32_e32 v134, 16, v75
	v_and_b32_e32 v135, 0xffff0000, v75
	v_pk_mul_f32 v[132:133], v[130:131], v[132:133] op_sel_hi:[0,1]
	v_pk_mul_f32 v[134:135], v[130:131], v[134:135] op_sel_hi:[0,1]
	v_pk_mul_f32 v[148:149], v[132:133], v[12:13]
	v_pk_mul_f32 v[150:151], v[134:135], v[14:15]
	global_store_dwordx4 v18, v[136:139], s[14:15] offset:0
	global_store_dwordx4 v18, v[140:143], s[14:15] offset:1024
	global_store_dwordx4 v18, v[144:147], s[14:15] offset:2048
	global_store_dwordx4 v18, v[148:151], s[14:15] offset:3072
	s_add_u32 s14, s14, 0x800000
	s_addc_u32 s15, s15, 0
	s_nop 1
	s_waitcnt vmcnt(36)
	global_load_dwordx2 v[56:57], v17, s[10:11] offset:0
	global_load_dwordx2 v[58:59], v17, s[10:11] offset:512
	global_load_dwordx2 v[60:61], v17, s[10:11] offset:1024
	global_load_dwordx2 v[62:63], v17, s[10:11] offset:1536
	global_load_dwordx4 v[64:67], v19, s[12:13]
	s_add_u32 s10, s10, 0x400000
	s_addc_u32 s11, s11, 0
	s_add_u32 s12, s12, 0x8000
	s_addc_u32 s13, s13, 0
	global_load_dwordx2 v[68:69], v17, s[10:11] offset:0
	global_load_dwordx2 v[70:71], v17, s[10:11] offset:512
	global_load_dwordx2 v[72:73], v17, s[10:11] offset:1024
	global_load_dwordx2 v[74:75], v17, s[10:11] offset:1536
	global_load_dwordx4 v[76:79], v19, s[12:13]
	s_add_u32 s10, s10, 0x400000
	s_addc_u32 s11, s11, 0
	s_add_u32 s12, s12, 0x8000
	s_addc_u32 s13, s13, 0
	v_add_f32_e32 v128, v88, v89
	v_add_f32_e32 v129, v90, v91
	v_add_f32_e32 v128, v128, v129
	v_fmamk_f32 v128, v128, 0x3a800000, v20
	v_rsq_f32_e32 v130, v128
	v_lshlrev_b32_e32 v132, 16, v80
	v_and_b32_e32 v133, 0xffff0000, v80
	v_lshlrev_b32_e32 v134, 16, v81
	v_and_b32_e32 v135, 0xffff0000, v81
	v_pk_mul_f32 v[132:133], v[130:131], v[132:133] op_sel_hi:[0,1]
	v_pk_mul_f32 v[134:135], v[130:131], v[134:135] op_sel_hi:[0,1]
	v_pk_mul_f32 v[136:137], v[132:133], v[0:1]
	v_pk_mul_f32 v[138:139], v[134:135], v[2:3]
	v_lshlrev_b32_e32 v132, 16, v82
	v_and_b32_e32 v133, 0xffff0000, v82
	v_lshlrev_b32_e32 v134, 16, v83
	v_and_b32_e32 v135, 0xffff0000, v83
	v_pk_mul_f32 v[132:133], v[130:131], v[132:133] op_sel_hi:[0,1]
	v_pk_mul_f32 v[134:135], v[130:131], v[134:135] op_sel_hi:[0,1]
	v_pk_mul_f32 v[140:141], v[132:133], v[4:5]
	v_pk_mul_f32 v[142:143], v[134:135], v[6:7]
	v_lshlrev_b32_e32 v132, 16, v84
	v_and_b32_e32 v133, 0xffff0000, v84
	v_lshlrev_b32_e32 v134, 16, v85
	v_and_b32_e32 v135, 0xffff0000, v85
	v_pk_mul_f32 v[132:133], v[130:131], v[132:133] op_sel_hi:[0,1]
	v_pk_mul_f32 v[134:135], v[130:131], v[134:135] op_sel_hi:[0,1]
	v_pk_mul_f32 v[144:145], v[132:133], v[8:9]
	v_pk_mul_f32 v[146:147], v[134:135], v[10:11]
	v_lshlrev_b32_e32 v132, 16, v86
	v_and_b32_e32 v133, 0xffff0000, v86
	v_lshlrev_b32_e32 v134, 16, v87
	v_and_b32_e32 v135, 0xffff0000, v87
	v_pk_mul_f32 v[132:133], v[130:131], v[132:133] op_sel_hi:[0,1]
	v_pk_mul_f32 v[134:135], v[130:131], v[134:135] op_sel_hi:[0,1]
	v_pk_mul_f32 v[148:149], v[132:133], v[12:13]
	v_pk_mul_f32 v[150:151], v[134:135], v[14:15]
	global_store_dwordx4 v18, v[136:139], s[14:15] offset:0
	global_store_dwordx4 v18, v[140:143], s[14:15] offset:1024
	global_store_dwordx4 v18, v[144:147], s[14:15] offset:2048
	global_store_dwordx4 v18, v[148:151], s[14:15] offset:3072
	s_add_u32 s14, s14, 0x800000
	s_addc_u32 s15, s15, 0
	s_nop 1
	v_add_f32_e32 v128, v100, v101
	v_add_f32_e32 v129, v102, v103
	v_add_f32_e32 v128, v128, v129
	v_fmamk_f32 v128, v128, 0x3a800000, v20
	v_rsq_f32_e32 v130, v128
	v_lshlrev_b32_e32 v132, 16, v92
	v_and_b32_e32 v133, 0xffff0000, v92
	v_lshlrev_b32_e32 v134, 16, v93
	v_and_b32_e32 v135, 0xffff0000, v93
	v_pk_mul_f32 v[132:133], v[130:131], v[132:133] op_sel_hi:[0,1]
	v_pk_mul_f32 v[134:135], v[130:131], v[134:135] op_sel_hi:[0,1]
	v_pk_mul_f32 v[136:137], v[132:133], v[0:1]
	v_pk_mul_f32 v[138:139], v[134:135], v[2:3]
	v_lshlrev_b32_e32 v132, 16, v94
	v_and_b32_e32 v133, 0xffff0000, v94
	v_lshlrev_b32_e32 v134, 16, v95
	v_and_b32_e32 v135, 0xffff0000, v95
	v_pk_mul_f32 v[132:133], v[130:131], v[132:133] op_sel_hi:[0,1]
	v_pk_mul_f32 v[134:135], v[130:131], v[134:135] op_sel_hi:[0,1]
	v_pk_mul_f32 v[140:141], v[132:133], v[4:5]
	v_pk_mul_f32 v[142:143], v[134:135], v[6:7]
	v_lshlrev_b32_e32 v132, 16, v96
	v_and_b32_e32 v133, 0xffff0000, v96
	v_lshlrev_b32_e32 v134, 16, v97
	v_and_b32_e32 v135, 0xffff0000, v97
	v_pk_mul_f32 v[132:133], v[130:131], v[132:133] op_sel_hi:[0,1]
	v_pk_mul_f32 v[134:135], v[130:131], v[134:135] op_sel_hi:[0,1]
	v_pk_mul_f32 v[144:145], v[132:133], v[8:9]
	v_pk_mul_f32 v[146:147], v[134:135], v[10:11]
	v_lshlrev_b32_e32 v132, 16, v98
	v_and_b32_e32 v133, 0xffff0000, v98
	v_lshlrev_b32_e32 v134, 16, v99
	v_and_b32_e32 v135, 0xffff0000, v99
	v_pk_mul_f32 v[132:133], v[130:131], v[132:133] op_sel_hi:[0,1]
	v_pk_mul_f32 v[134:135], v[130:131], v[134:135] op_sel_hi:[0,1]
	v_pk_mul_f32 v[148:149], v[132:133], v[12:13]
	v_pk_mul_f32 v[150:151], v[134:135], v[14:15]
	global_store_dwordx4 v18, v[136:139], s[14:15] offset:0
	global_store_dwordx4 v18, v[140:143], s[14:15] offset:1024
	global_store_dwordx4 v18, v[144:147], s[14:15] offset:2048
	global_store_dwordx4 v18, v[148:151], s[14:15] offset:3072
	s_add_u32 s14, s14, 0x800000
	s_addc_u32 s15, s15, 0
	s_nop 1
	s_waitcnt vmcnt(44)
	global_load_dwordx2 v[80:81], v17, s[10:11] offset:0
	global_load_dwordx2 v[82:83], v17, s[10:11] offset:512
	global_load_dwordx2 v[84:85], v17, s[10:11] offset:1024
	global_load_dwordx2 v[86:87], v17, s[10:11] offset:1536
	global_load_dwordx4 v[88:91], v19, s[12:13]
	s_add_u32 s10, s10, 0x400000
	s_addc_u32 s11, s11, 0
	s_add_u32 s12, s12, 0x8000
	s_addc_u32 s13, s13, 0
	global_load_dwordx2 v[92:93], v17, s[10:11] offset:0
	global_load_dwordx2 v[94:95], v17, s[10:11] offset:512
	global_load_dwordx2 v[96:97], v17, s[10:11] offset:1024
	global_load_dwordx2 v[98:99], v17, s[10:11] offset:1536
	global_load_dwordx4 v[100:103], v19, s[12:13]
	s_add_u32 s10, s10, 0x400000
	s_addc_u32 s11, s11, 0
	s_add_u32 s12, s12, 0x8000
	s_addc_u32 s13, s13, 0
	v_add_f32_e32 v128, v112, v113
	v_add_f32_e32 v129, v114, v115
	v_add_f32_e32 v128, v128, v129
	v_fmamk_f32 v128, v128, 0x3a800000, v20
	v_rsq_f32_e32 v130, v128
	v_lshlrev_b32_e32 v132, 16, v104
	v_and_b32_e32 v133, 0xffff0000, v104
	v_lshlrev_b32_e32 v134, 16, v105
	v_and_b32_e32 v135, 0xffff0000, v105
	v_pk_mul_f32 v[132:133], v[130:131], v[132:133] op_sel_hi:[0,1]
	v_pk_mul_f32 v[134:135], v[130:131], v[134:135] op_sel_hi:[0,1]
	v_pk_mul_f32 v[136:137], v[132:133], v[0:1]
	v_pk_mul_f32 v[138:139], v[134:135], v[2:3]
	v_lshlrev_b32_e32 v132, 16, v106
	v_and_b32_e32 v133, 0xffff0000, v106
	v_lshlrev_b32_e32 v134, 16, v107
	v_and_b32_e32 v135, 0xffff0000, v107
	v_pk_mul_f32 v[132:133], v[130:131], v[132:133] op_sel_hi:[0,1]
	v_pk_mul_f32 v[134:135], v[130:131], v[134:135] op_sel_hi:[0,1]
	v_pk_mul_f32 v[140:141], v[132:133], v[4:5]
	v_pk_mul_f32 v[142:143], v[134:135], v[6:7]
	v_lshlrev_b32_e32 v132, 16, v108
	v_and_b32_e32 v133, 0xffff0000, v108
	v_lshlrev_b32_e32 v134, 16, v109
	v_and_b32_e32 v135, 0xffff0000, v109
	v_pk_mul_f32 v[132:133], v[130:131], v[132:133] op_sel_hi:[0,1]
	v_pk_mul_f32 v[134:135], v[130:131], v[134:135] op_sel_hi:[0,1]
	v_pk_mul_f32 v[144:145], v[132:133], v[8:9]
	v_pk_mul_f32 v[146:147], v[134:135], v[10:11]
	v_lshlrev_b32_e32 v132, 16, v110
	v_and_b32_e32 v133, 0xffff0000, v110
	v_lshlrev_b32_e32 v134, 16, v111
	v_and_b32_e32 v135, 0xffff0000, v111
	v_pk_mul_f32 v[132:133], v[130:131], v[132:133] op_sel_hi:[0,1]
	v_pk_mul_f32 v[134:135], v[130:131], v[134:135] op_sel_hi:[0,1]
	v_pk_mul_f32 v[148:149], v[132:133], v[12:13]
	v_pk_mul_f32 v[150:151], v[134:135], v[14:15]
	global_store_dwordx4 v18, v[136:139], s[14:15] offset:0
	global_store_dwordx4 v18, v[140:143], s[14:15] offset:1024
	global_store_dwordx4 v18, v[144:147], s[14:15] offset:2048
	global_store_dwordx4 v18, v[148:151], s[14:15] offset:3072
	s_add_u32 s14, s14, 0x800000
	s_addc_u32 s15, s15, 0
	s_nop 1
	v_add_f32_e32 v128, v124, v125
	v_add_f32_e32 v129, v126, v127
	v_add_f32_e32 v128, v128, v129
	v_fmamk_f32 v128, v128, 0x3a800000, v20
	v_rsq_f32_e32 v130, v128
	v_lshlrev_b32_e32 v132, 16, v116
	v_and_b32_e32 v133, 0xffff0000, v116
	v_lshlrev_b32_e32 v134, 16, v117
	v_and_b32_e32 v135, 0xffff0000, v117
	v_pk_mul_f32 v[132:133], v[130:131], v[132:133] op_sel_hi:[0,1]
	v_pk_mul_f32 v[134:135], v[130:131], v[134:135] op_sel_hi:[0,1]
	v_pk_mul_f32 v[136:137], v[132:133], v[0:1]
	v_pk_mul_f32 v[138:139], v[134:135], v[2:3]
	v_lshlrev_b32_e32 v132, 16, v118
	v_and_b32_e32 v133, 0xffff0000, v118
	v_lshlrev_b32_e32 v134, 16, v119
	v_and_b32_e32 v135, 0xffff0000, v119
	v_pk_mul_f32 v[132:133], v[130:131], v[132:133] op_sel_hi:[0,1]
	v_pk_mul_f32 v[134:135], v[130:131], v[134:135] op_sel_hi:[0,1]
	v_pk_mul_f32 v[140:141], v[132:133], v[4:5]
	v_pk_mul_f32 v[142:143], v[134:135], v[6:7]
	v_lshlrev_b32_e32 v132, 16, v120
	v_and_b32_e32 v133, 0xffff0000, v120
	v_lshlrev_b32_e32 v134, 16, v121
	v_and_b32_e32 v135, 0xffff0000, v121
	v_pk_mul_f32 v[132:133], v[130:131], v[132:133] op_sel_hi:[0,1]
	v_pk_mul_f32 v[134:135], v[130:131], v[134:135] op_sel_hi:[0,1]
	v_pk_mul_f32 v[144:145], v[132:133], v[8:9]
	v_pk_mul_f32 v[146:147], v[134:135], v[10:11]
	v_lshlrev_b32_e32 v132, 16, v122
	v_and_b32_e32 v133, 0xffff0000, v122
	v_lshlrev_b32_e32 v134, 16, v123
	v_and_b32_e32 v135, 0xffff0000, v123
	v_pk_mul_f32 v[132:133], v[130:131], v[132:133] op_sel_hi:[0,1]
	v_pk_mul_f32 v[134:135], v[130:131], v[134:135] op_sel_hi:[0,1]
	v_pk_mul_f32 v[148:149], v[132:133], v[12:13]
	v_pk_mul_f32 v[150:151], v[134:135], v[14:15]
	global_store_dwordx4 v18, v[136:139], s[14:15] offset:0
	global_store_dwordx4 v18, v[140:143], s[14:15] offset:1024
	global_store_dwordx4 v18, v[144:147], s[14:15] offset:2048
	global_store_dwordx4 v18, v[148:151], s[14:15] offset:3072
	s_add_u32 s14, s14, 0x800000
	s_addc_u32 s15, s15, 0
	s_nop 1
	s_waitcnt vmcnt(44)
	global_load_dwordx2 v[104:105], v17, s[10:11] offset:0
	global_load_dwordx2 v[106:107], v17, s[10:11] offset:512
	global_load_dwordx2 v[108:109], v17, s[10:11] offset:1024
	global_load_dwordx2 v[110:111], v17, s[10:11] offset:1536
	global_load_dwordx4 v[112:115], v19, s[12:13]
	s_add_u32 s10, s10, 0x400000
	s_addc_u32 s11, s11, 0
	s_add_u32 s12, s12, 0x8000
	s_addc_u32 s13, s13, 0
	global_load_dwordx2 v[116:117], v17, s[10:11] offset:0
	global_load_dwordx2 v[118:119], v17, s[10:11] offset:512
	global_load_dwordx2 v[120:121], v17, s[10:11] offset:1024
	global_load_dwordx2 v[122:123], v17, s[10:11] offset:1536
	global_load_dwordx4 v[124:127], v19, s[12:13]
	s_add_u32 s10, s10, 0x400000
	s_addc_u32 s11, s11, 0
	s_add_u32 s12, s12, 0x8000
	s_addc_u32 s13, s13, 0
	v_add_f32_e32 v128, v40, v41
	v_add_f32_e32 v129, v42, v43
	v_add_f32_e32 v128, v128, v129
	v_fmamk_f32 v128, v128, 0x3a800000, v20
	v_rsq_f32_e32 v130, v128
	v_lshlrev_b32_e32 v132, 16, v32
	v_and_b32_e32 v133, 0xffff0000, v32
	v_lshlrev_b32_e32 v134, 16, v33
	v_and_b32_e32 v135, 0xffff0000, v33
	v_pk_mul_f32 v[132:133], v[130:131], v[132:133] op_sel_hi:[0,1]
	v_pk_mul_f32 v[134:135], v[130:131], v[134:135] op_sel_hi:[0,1]
	v_pk_mul_f32 v[136:137], v[132:133], v[0:1]
	v_pk_mul_f32 v[138:139], v[134:135], v[2:3]
	v_lshlrev_b32_e32 v132, 16, v34
	v_and_b32_e32 v133, 0xffff0000, v34
	v_lshlrev_b32_e32 v134, 16, v35
	v_and_b32_e32 v135, 0xffff0000, v35
	v_pk_mul_f32 v[132:133], v[130:131], v[132:133] op_sel_hi:[0,1]
	v_pk_mul_f32 v[134:135], v[130:131], v[134:135] op_sel_hi:[0,1]
	v_pk_mul_f32 v[140:141], v[132:133], v[4:5]
	v_pk_mul_f32 v[142:143], v[134:135], v[6:7]
	v_lshlrev_b32_e32 v132, 16, v36
	v_and_b32_e32 v133, 0xffff0000, v36
	v_lshlrev_b32_e32 v134, 16, v37
	v_and_b32_e32 v135, 0xffff0000, v37
	v_pk_mul_f32 v[132:133], v[130:131], v[132:133] op_sel_hi:[0,1]
	v_pk_mul_f32 v[134:135], v[130:131], v[134:135] op_sel_hi:[0,1]
	v_pk_mul_f32 v[144:145], v[132:133], v[8:9]
	v_pk_mul_f32 v[146:147], v[134:135], v[10:11]
	v_lshlrev_b32_e32 v132, 16, v38
	v_and_b32_e32 v133, 0xffff0000, v38
	v_lshlrev_b32_e32 v134, 16, v39
	v_and_b32_e32 v135, 0xffff0000, v39
	v_pk_mul_f32 v[132:133], v[130:131], v[132:133] op_sel_hi:[0,1]
	v_pk_mul_f32 v[134:135], v[130:131], v[134:135] op_sel_hi:[0,1]
	v_pk_mul_f32 v[148:149], v[132:133], v[12:13]
	v_pk_mul_f32 v[150:151], v[134:135], v[14:15]
	global_store_dwordx4 v18, v[136:139], s[14:15] offset:0
	global_store_dwordx4 v18, v[140:143], s[14:15] offset:1024
	global_store_dwordx4 v18, v[144:147], s[14:15] offset:2048
	global_store_dwordx4 v18, v[148:151], s[14:15] offset:3072
	s_add_u32 s14, s14, 0x800000
	s_addc_u32 s15, s15, 0
	s_nop 1
	v_add_f32_e32 v128, v52, v53
	v_add_f32_e32 v129, v54, v55
	v_add_f32_e32 v128, v128, v129
	v_fmamk_f32 v128, v128, 0x3a800000, v20
	v_rsq_f32_e32 v130, v128
	v_lshlrev_b32_e32 v132, 16, v44
	v_and_b32_e32 v133, 0xffff0000, v44
	v_lshlrev_b32_e32 v134, 16, v45
	v_and_b32_e32 v135, 0xffff0000, v45
	v_pk_mul_f32 v[132:133], v[130:131], v[132:133] op_sel_hi:[0,1]
	v_pk_mul_f32 v[134:135], v[130:131], v[134:135] op_sel_hi:[0,1]
	v_pk_mul_f32 v[136:137], v[132:133], v[0:1]
	v_pk_mul_f32 v[138:139], v[134:135], v[2:3]
	v_lshlrev_b32_e32 v132, 16, v46
	v_and_b32_e32 v133, 0xffff0000, v46
	v_lshlrev_b32_e32 v134, 16, v47
	v_and_b32_e32 v135, 0xffff0000, v47
	v_pk_mul_f32 v[132:133], v[130:131], v[132:133] op_sel_hi:[0,1]
	v_pk_mul_f32 v[134:135], v[130:131], v[134:135] op_sel_hi:[0,1]
	v_pk_mul_f32 v[140:141], v[132:133], v[4:5]
	v_pk_mul_f32 v[142:143], v[134:135], v[6:7]
	v_lshlrev_b32_e32 v132, 16, v48
	v_and_b32_e32 v133, 0xffff0000, v48
	v_lshlrev_b32_e32 v134, 16, v49
	v_and_b32_e32 v135, 0xffff0000, v49
	v_pk_mul_f32 v[132:133], v[130:131], v[132:133] op_sel_hi:[0,1]
	v_pk_mul_f32 v[134:135], v[130:131], v[134:135] op_sel_hi:[0,1]
	v_pk_mul_f32 v[144:145], v[132:133], v[8:9]
	v_pk_mul_f32 v[146:147], v[134:135], v[10:11]
	v_lshlrev_b32_e32 v132, 16, v50
	v_and_b32_e32 v133, 0xffff0000, v50
	v_lshlrev_b32_e32 v134, 16, v51
	v_and_b32_e32 v135, 0xffff0000, v51
	v_pk_mul_f32 v[132:133], v[130:131], v[132:133] op_sel_hi:[0,1]
	v_pk_mul_f32 v[134:135], v[130:131], v[134:135] op_sel_hi:[0,1]
	v_pk_mul_f32 v[148:149], v[132:133], v[12:13]
	v_pk_mul_f32 v[150:151], v[134:135], v[14:15]
	global_store_dwordx4 v18, v[136:139], s[14:15] offset:0
	global_store_dwordx4 v18, v[140:143], s[14:15] offset:1024
	global_store_dwordx4 v18, v[144:147], s[14:15] offset:2048
	global_store_dwordx4 v18, v[148:151], s[14:15] offset:3072
	s_add_u32 s14, s14, 0x800000
	s_addc_u32 s15, s15, 0
	s_nop 1
	s_waitcnt vmcnt(44)
	v_add_f32_e32 v128, v64, v65
	v_add_f32_e32 v129, v66, v67
	v_add_f32_e32 v128, v128, v129
	v_fmamk_f32 v128, v128, 0x3a800000, v20
	v_rsq_f32_e32 v130, v128
	v_lshlrev_b32_e32 v132, 16, v56
	v_and_b32_e32 v133, 0xffff0000, v56
	v_lshlrev_b32_e32 v134, 16, v57
	v_and_b32_e32 v135, 0xffff0000, v57
	v_pk_mul_f32 v[132:133], v[130:131], v[132:133] op_sel_hi:[0,1]
	v_pk_mul_f32 v[134:135], v[130:131], v[134:135] op_sel_hi:[0,1]
	v_pk_mul_f32 v[136:137], v[132:133], v[0:1]
	v_pk_mul_f32 v[138:139], v[134:135], v[2:3]
	v_lshlrev_b32_e32 v132, 16, v58
	v_and_b32_e32 v133, 0xffff0000, v58
	v_lshlrev_b32_e32 v134, 16, v59
	v_and_b32_e32 v135, 0xffff0000, v59
	v_pk_mul_f32 v[132:133], v[130:131], v[132:133] op_sel_hi:[0,1]
	v_pk_mul_f32 v[134:135], v[130:131], v[134:135] op_sel_hi:[0,1]
	v_pk_mul_f32 v[140:141], v[132:133], v[4:5]
	v_pk_mul_f32 v[142:143], v[134:135], v[6:7]
	v_lshlrev_b32_e32 v132, 16, v60
	v_and_b32_e32 v133, 0xffff0000, v60
	v_lshlrev_b32_e32 v134, 16, v61
	v_and_b32_e32 v135, 0xffff0000, v61
	v_pk_mul_f32 v[132:133], v[130:131], v[132:133] op_sel_hi:[0,1]
	v_pk_mul_f32 v[134:135], v[130:131], v[134:135] op_sel_hi:[0,1]
	v_pk_mul_f32 v[144:145], v[132:133], v[8:9]
	v_pk_mul_f32 v[146:147], v[134:135], v[10:11]
	v_lshlrev_b32_e32 v132, 16, v62
	v_and_b32_e32 v133, 0xffff0000, v62
	v_lshlrev_b32_e32 v134, 16, v63
	v_and_b32_e32 v135, 0xffff0000, v63
	v_pk_mul_f32 v[132:133], v[130:131], v[132:133] op_sel_hi:[0,1]
	v_pk_mul_f32 v[134:135], v[130:131], v[134:135] op_sel_hi:[0,1]
	v_pk_mul_f32 v[148:149], v[132:133], v[12:13]
	v_pk_mul_f32 v[150:151], v[134:135], v[14:15]
	global_store_dwordx4 v18, v[136:139], s[14:15] offset:0
	global_store_dwordx4 v18, v[140:143], s[14:15] offset:1024
	global_store_dwordx4 v18, v[144:147], s[14:15] offset:2048
	global_store_dwordx4 v18, v[148:151], s[14:15] offset:3072
	s_add_u32 s14, s14, 0x800000
	s_addc_u32 s15, s15, 0
	s_nop 1
	v_add_f32_e32 v128, v76, v77
	v_add_f32_e32 v129, v78, v79
	v_add_f32_e32 v128, v128, v129
	v_fmamk_f32 v128, v128, 0x3a800000, v20
	v_rsq_f32_e32 v130, v128
	v_lshlrev_b32_e32 v132, 16, v68
	v_and_b32_e32 v133, 0xffff0000, v68
	v_lshlrev_b32_e32 v134, 16, v69
	v_and_b32_e32 v135, 0xffff0000, v69
	v_pk_mul_f32 v[132:133], v[130:131], v[132:133] op_sel_hi:[0,1]
	v_pk_mul_f32 v[134:135], v[130:131], v[134:135] op_sel_hi:[0,1]
	v_pk_mul_f32 v[136:137], v[132:133], v[0:1]
	v_pk_mul_f32 v[138:139], v[134:135], v[2:3]
	v_lshlrev_b32_e32 v132, 16, v70
	v_and_b32_e32 v133, 0xffff0000, v70
	v_lshlrev_b32_e32 v134, 16, v71
	v_and_b32_e32 v135, 0xffff0000, v71
	v_pk_mul_f32 v[132:133], v[130:131], v[132:133] op_sel_hi:[0,1]
	v_pk_mul_f32 v[134:135], v[130:131], v[134:135] op_sel_hi:[0,1]
	v_pk_mul_f32 v[140:141], v[132:133], v[4:5]
	v_pk_mul_f32 v[142:143], v[134:135], v[6:7]
	v_lshlrev_b32_e32 v132, 16, v72
	v_and_b32_e32 v133, 0xffff0000, v72
	v_lshlrev_b32_e32 v134, 16, v73
	v_and_b32_e32 v135, 0xffff0000, v73
	v_pk_mul_f32 v[132:133], v[130:131], v[132:133] op_sel_hi:[0,1]
	v_pk_mul_f32 v[134:135], v[130:131], v[134:135] op_sel_hi:[0,1]
	v_pk_mul_f32 v[144:145], v[132:133], v[8:9]
	v_pk_mul_f32 v[146:147], v[134:135], v[10:11]
	v_lshlrev_b32_e32 v132, 16, v74
	v_and_b32_e32 v133, 0xffff0000, v74
	v_lshlrev_b32_e32 v134, 16, v75
	v_and_b32_e32 v135, 0xffff0000, v75
	v_pk_mul_f32 v[132:133], v[130:131], v[132:133] op_sel_hi:[0,1]
	v_pk_mul_f32 v[134:135], v[130:131], v[134:135] op_sel_hi:[0,1]
	v_pk_mul_f32 v[148:149], v[132:133], v[12:13]
	v_pk_mul_f32 v[150:151], v[134:135], v[14:15]
	global_store_dwordx4 v18, v[136:139], s[14:15] offset:0
	global_store_dwordx4 v18, v[140:143], s[14:15] offset:1024
	global_store_dwordx4 v18, v[144:147], s[14:15] offset:2048
	global_store_dwordx4 v18, v[148:151], s[14:15] offset:3072
	s_add_u32 s14, s14, 0x800000
	s_addc_u32 s15, s15, 0
	s_nop 1
	s_waitcnt vmcnt(34)
	v_add_f32_e32 v128, v88, v89
	v_add_f32_e32 v129, v90, v91
	v_add_f32_e32 v128, v128, v129
	v_fmamk_f32 v128, v128, 0x3a800000, v20
	v_rsq_f32_e32 v130, v128
	v_lshlrev_b32_e32 v132, 16, v80
	v_and_b32_e32 v133, 0xffff0000, v80
	v_lshlrev_b32_e32 v134, 16, v81
	v_and_b32_e32 v135, 0xffff0000, v81
	v_pk_mul_f32 v[132:133], v[130:131], v[132:133] op_sel_hi:[0,1]
	v_pk_mul_f32 v[134:135], v[130:131], v[134:135] op_sel_hi:[0,1]
	v_pk_mul_f32 v[136:137], v[132:133], v[0:1]
	v_pk_mul_f32 v[138:139], v[134:135], v[2:3]
	v_lshlrev_b32_e32 v132, 16, v82
	v_and_b32_e32 v133, 0xffff0000, v82
	v_lshlrev_b32_e32 v134, 16, v83
	v_and_b32_e32 v135, 0xffff0000, v83
	v_pk_mul_f32 v[132:133], v[130:131], v[132:133] op_sel_hi:[0,1]
	v_pk_mul_f32 v[134:135], v[130:131], v[134:135] op_sel_hi:[0,1]
	v_pk_mul_f32 v[140:141], v[132:133], v[4:5]
	v_pk_mul_f32 v[142:143], v[134:135], v[6:7]
	v_lshlrev_b32_e32 v132, 16, v84
	v_and_b32_e32 v133, 0xffff0000, v84
	v_lshlrev_b32_e32 v134, 16, v85
	v_and_b32_e32 v135, 0xffff0000, v85
	v_pk_mul_f32 v[132:133], v[130:131], v[132:133] op_sel_hi:[0,1]
	v_pk_mul_f32 v[134:135], v[130:131], v[134:135] op_sel_hi:[0,1]
	v_pk_mul_f32 v[144:145], v[132:133], v[8:9]
	v_pk_mul_f32 v[146:147], v[134:135], v[10:11]
	v_lshlrev_b32_e32 v132, 16, v86
	v_and_b32_e32 v133, 0xffff0000, v86
	v_lshlrev_b32_e32 v134, 16, v87
	v_and_b32_e32 v135, 0xffff0000, v87
	v_pk_mul_f32 v[132:133], v[130:131], v[132:133] op_sel_hi:[0,1]
	v_pk_mul_f32 v[134:135], v[130:131], v[134:135] op_sel_hi:[0,1]
	v_pk_mul_f32 v[148:149], v[132:133], v[12:13]
	v_pk_mul_f32 v[150:151], v[134:135], v[14:15]
	global_store_dwordx4 v18, v[136:139], s[14:15] offset:0
	global_store_dwordx4 v18, v[140:143], s[14:15] offset:1024
	global_store_dwordx4 v18, v[144:147], s[14:15] offset:2048
	global_store_dwordx4 v18, v[148:151], s[14:15] offset:3072
	s_add_u32 s14, s14, 0x800000
	s_addc_u32 s15, s15, 0
	s_nop 1
	v_add_f32_e32 v128, v100, v101
	v_add_f32_e32 v129, v102, v103
	v_add_f32_e32 v128, v128, v129
	v_fmamk_f32 v128, v128, 0x3a800000, v20
	v_rsq_f32_e32 v130, v128
	v_lshlrev_b32_e32 v132, 16, v92
	v_and_b32_e32 v133, 0xffff0000, v92
	v_lshlrev_b32_e32 v134, 16, v93
	v_and_b32_e32 v135, 0xffff0000, v93
	v_pk_mul_f32 v[132:133], v[130:131], v[132:133] op_sel_hi:[0,1]
	v_pk_mul_f32 v[134:135], v[130:131], v[134:135] op_sel_hi:[0,1]
	v_pk_mul_f32 v[136:137], v[132:133], v[0:1]
	v_pk_mul_f32 v[138:139], v[134:135], v[2:3]
	v_lshlrev_b32_e32 v132, 16, v94
	v_and_b32_e32 v133, 0xffff0000, v94
	v_lshlrev_b32_e32 v134, 16, v95
	v_and_b32_e32 v135, 0xffff0000, v95
	v_pk_mul_f32 v[132:133], v[130:131], v[132:133] op_sel_hi:[0,1]
	v_pk_mul_f32 v[134:135], v[130:131], v[134:135] op_sel_hi:[0,1]
	v_pk_mul_f32 v[140:141], v[132:133], v[4:5]
	v_pk_mul_f32 v[142:143], v[134:135], v[6:7]
	v_lshlrev_b32_e32 v132, 16, v96
	v_and_b32_e32 v133, 0xffff0000, v96
	v_lshlrev_b32_e32 v134, 16, v97
	v_and_b32_e32 v135, 0xffff0000, v97
	v_pk_mul_f32 v[132:133], v[130:131], v[132:133] op_sel_hi:[0,1]
	v_pk_mul_f32 v[134:135], v[130:131], v[134:135] op_sel_hi:[0,1]
	v_pk_mul_f32 v[144:145], v[132:133], v[8:9]
	v_pk_mul_f32 v[146:147], v[134:135], v[10:11]
	v_lshlrev_b32_e32 v132, 16, v98
	v_and_b32_e32 v133, 0xffff0000, v98
	v_lshlrev_b32_e32 v134, 16, v99
	v_and_b32_e32 v135, 0xffff0000, v99
	v_pk_mul_f32 v[132:133], v[130:131], v[132:133] op_sel_hi:[0,1]
	v_pk_mul_f32 v[134:135], v[130:131], v[134:135] op_sel_hi:[0,1]
	v_pk_mul_f32 v[148:149], v[132:133], v[12:13]
	v_pk_mul_f32 v[150:151], v[134:135], v[14:15]
	global_store_dwordx4 v18, v[136:139], s[14:15] offset:0
	global_store_dwordx4 v18, v[140:143], s[14:15] offset:1024
	global_store_dwordx4 v18, v[144:147], s[14:15] offset:2048
	global_store_dwordx4 v18, v[148:151], s[14:15] offset:3072
	s_add_u32 s14, s14, 0x800000
	s_addc_u32 s15, s15, 0
	s_nop 1
	s_waitcnt vmcnt(24)
	v_add_f32_e32 v128, v112, v113
	v_add_f32_e32 v129, v114, v115
	v_add_f32_e32 v128, v128, v129
	v_fmamk_f32 v128, v128, 0x3a800000, v20
	v_rsq_f32_e32 v130, v128
	v_lshlrev_b32_e32 v132, 16, v104
	v_and_b32_e32 v133, 0xffff0000, v104
	v_lshlrev_b32_e32 v134, 16, v105
	v_and_b32_e32 v135, 0xffff0000, v105
	v_pk_mul_f32 v[132:133], v[130:131], v[132:133] op_sel_hi:[0,1]
	v_pk_mul_f32 v[134:135], v[130:131], v[134:135] op_sel_hi:[0,1]
	v_pk_mul_f32 v[136:137], v[132:133], v[0:1]
	v_pk_mul_f32 v[138:139], v[134:135], v[2:3]
	v_lshlrev_b32_e32 v132, 16, v106
	v_and_b32_e32 v133, 0xffff0000, v106
	v_lshlrev_b32_e32 v134, 16, v107
	v_and_b32_e32 v135, 0xffff0000, v107
	v_pk_mul_f32 v[132:133], v[130:131], v[132:133] op_sel_hi:[0,1]
	v_pk_mul_f32 v[134:135], v[130:131], v[134:135] op_sel_hi:[0,1]
	v_pk_mul_f32 v[140:141], v[132:133], v[4:5]
	v_pk_mul_f32 v[142:143], v[134:135], v[6:7]
	v_lshlrev_b32_e32 v132, 16, v108
	v_and_b32_e32 v133, 0xffff0000, v108
	v_lshlrev_b32_e32 v134, 16, v109
	v_and_b32_e32 v135, 0xffff0000, v109
	v_pk_mul_f32 v[132:133], v[130:131], v[132:133] op_sel_hi:[0,1]
	v_pk_mul_f32 v[134:135], v[130:131], v[134:135] op_sel_hi:[0,1]
	v_pk_mul_f32 v[144:145], v[132:133], v[8:9]
	v_pk_mul_f32 v[146:147], v[134:135], v[10:11]
	v_lshlrev_b32_e32 v132, 16, v110
	v_and_b32_e32 v133, 0xffff0000, v110
	v_lshlrev_b32_e32 v134, 16, v111
	v_and_b32_e32 v135, 0xffff0000, v111
	v_pk_mul_f32 v[132:133], v[130:131], v[132:133] op_sel_hi:[0,1]
	v_pk_mul_f32 v[134:135], v[130:131], v[134:135] op_sel_hi:[0,1]
	v_pk_mul_f32 v[148:149], v[132:133], v[12:13]
	v_pk_mul_f32 v[150:151], v[134:135], v[14:15]
	global_store_dwordx4 v18, v[136:139], s[14:15] offset:0
	global_store_dwordx4 v18, v[140:143], s[14:15] offset:1024
	global_store_dwordx4 v18, v[144:147], s[14:15] offset:2048
	global_store_dwordx4 v18, v[148:151], s[14:15] offset:3072
	s_add_u32 s14, s14, 0x800000
	s_addc_u32 s15, s15, 0
	s_nop 1
	v_add_f32_e32 v128, v124, v125
	v_add_f32_e32 v129, v126, v127
	v_add_f32_e32 v128, v128, v129
	v_fmamk_f32 v128, v128, 0x3a800000, v20
	v_rsq_f32_e32 v130, v128
	v_lshlrev_b32_e32 v132, 16, v116
	v_and_b32_e32 v133, 0xffff0000, v116
	v_lshlrev_b32_e32 v134, 16, v117
	v_and_b32_e32 v135, 0xffff0000, v117
	v_pk_mul_f32 v[132:133], v[130:131], v[132:133] op_sel_hi:[0,1]
	v_pk_mul_f32 v[134:135], v[130:131], v[134:135] op_sel_hi:[0,1]
	v_pk_mul_f32 v[136:137], v[132:133], v[0:1]
	v_pk_mul_f32 v[138:139], v[134:135], v[2:3]
	v_lshlrev_b32_e32 v132, 16, v118
	v_and_b32_e32 v133, 0xffff0000, v118
	v_lshlrev_b32_e32 v134, 16, v119
	v_and_b32_e32 v135, 0xffff0000, v119
	v_pk_mul_f32 v[132:133], v[130:131], v[132:133] op_sel_hi:[0,1]
	v_pk_mul_f32 v[134:135], v[130:131], v[134:135] op_sel_hi:[0,1]
	v_pk_mul_f32 v[140:141], v[132:133], v[4:5]
	v_pk_mul_f32 v[142:143], v[134:135], v[6:7]
	v_lshlrev_b32_e32 v132, 16, v120
	v_and_b32_e32 v133, 0xffff0000, v120
	v_lshlrev_b32_e32 v134, 16, v121
	v_and_b32_e32 v135, 0xffff0000, v121
	v_pk_mul_f32 v[132:133], v[130:131], v[132:133] op_sel_hi:[0,1]
	v_pk_mul_f32 v[134:135], v[130:131], v[134:135] op_sel_hi:[0,1]
	v_pk_mul_f32 v[144:145], v[132:133], v[8:9]
	v_pk_mul_f32 v[146:147], v[134:135], v[10:11]
	v_lshlrev_b32_e32 v132, 16, v122
	v_and_b32_e32 v133, 0xffff0000, v122
	v_lshlrev_b32_e32 v134, 16, v123
	v_and_b32_e32 v135, 0xffff0000, v123
	v_pk_mul_f32 v[132:133], v[130:131], v[132:133] op_sel_hi:[0,1]
	v_pk_mul_f32 v[134:135], v[130:131], v[134:135] op_sel_hi:[0,1]
	v_pk_mul_f32 v[148:149], v[132:133], v[12:13]
	v_pk_mul_f32 v[150:151], v[134:135], v[14:15]
	global_store_dwordx4 v18, v[136:139], s[14:15] offset:0
	global_store_dwordx4 v18, v[140:143], s[14:15] offset:1024
	global_store_dwordx4 v18, v[144:147], s[14:15] offset:2048
	global_store_dwordx4 v18, v[148:151], s[14:15] offset:3072
	s_add_u32 s14, s14, 0x800000
	s_addc_u32 s15, s15, 0
	s_nop 1
	s_branch .LBB0_988
